# m30 + step A loop head: counted waits on the four key-fragment loads (vmcnt 3, 1, 0 at their first MFMA users) instead of one vmcnt(0)
# speedup vs baseline: 1.0045x; 1.0045x over previous
.LBB0_1296:
	s_add_i32 s8, s3, s17
	s_add_i32 s0, s18, 1
	s_add_i32 s9, s8, 8
	s_cmp_lt_i32 s0, s13
	s_cselect_b64 s[0:1], -1, 0
	s_and_b64 vcc, s[0:1], exec
	s_cselect_b32 s10, s9, s8
	s_add_i32 s9, s8, 16
	s_cmp_lt_i32 s18, s14
	s_cselect_b32 s9, s9, s8
	s_add_i32 s8, s8, 24
	s_cmp_lt_i32 s18, s15
	s_cselect_b32 s11, s8, s9
	s_lshl_b32 s68, s9, 4
	s_lshl_b64 s[8:9], s[68:69], 7
	ds_read_b128 v[22:25], v174
	ds_read_b128 v[18:21], v174 offset:1024
	s_waitcnt vmcnt(3) lgkmcnt(2)
	v_mfma_f32_16x16x32_bf16 v[230:233], v[6:9], v[200:203], 0
	ds_read_b128 v[178:181], v173 offset:6144
	ds_read_b128 v[182:185], v173 offset:7168
	s_waitcnt vmcnt(1)
	v_mfma_f32_16x16x32_bf16 v[234:237], v[14:17], v[200:203], 0
	v_mfma_f32_16x16x32_bf16 v[230:233], v[2:5], v[204:207], v[230:233]
	s_nop 2
	s_waitcnt vmcnt(0)
	v_mfma_f32_16x16x32_bf16 v[234:237], v[10:13], v[204:207], v[234:237]
	s_waitcnt lgkmcnt(2)
	v_mfma_f32_16x16x32_bf16 v[238:241], v[6:9], v[208:211], 0
	ds_read_b128 v[200:203], v173 offset:8192
	ds_read_b128 v[204:207], v173 offset:9216
	v_max_i32_e32 v250, 0, v230
	v_fma_f32 v34, v250, v22, 0
	v_max_i32_e32 v225, 0, v231
	v_fma_f32 v35, v225, v22, 0
	v_mfma_f32_16x16x32_bf16 v[242:245], v[14:17], v[208:211], 0
	v_max_i32_e32 v250, 0, v232
	v_fma_f32 v32, v250, v22, 0
	v_max_i32_e32 v225, 0, v233
	v_fma_f32 v33, v225, v22, 0
	v_mfma_f32_16x16x32_bf16 v[238:241], v[2:5], v[212:215], v[238:241]
	v_max_i32_e32 v250, 0, v234
	v_fma_f32 v30, v250, v22, 0
	v_max_i32_e32 v225, 0, v235
	v_fma_f32 v31, v225, v22, 0
	v_mfma_f32_16x16x32_bf16 v[242:245], v[10:13], v[212:215], v[242:245]
	v_max_i32_e32 v250, 0, v236
	v_fma_f32 v28, v250, v22, 0
	v_max_i32_e32 v225, 0, v237
	v_fma_f32 v29, v225, v22, 0
	v_mfma_f32_16x16x32_bf16 v[230:233], v[6:9], v[216:219], 0
	ds_read_b128 v[208:211], v173 offset:10240
	ds_read_b128 v[212:215], v173 offset:11264
	v_max_i32_e32 v250, 0, v238
	v_fmac_f32_e32 v34, v250, v23
	v_max_i32_e32 v225, 0, v239
	v_fmac_f32_e32 v35, v225, v23
	v_mfma_f32_16x16x32_bf16 v[234:237], v[14:17], v[216:219], 0
	v_max_i32_e32 v250, 0, v240
	v_fmac_f32_e32 v32, v250, v23
	v_max_i32_e32 v225, 0, v241
	v_fmac_f32_e32 v33, v225, v23
	v_mfma_f32_16x16x32_bf16 v[230:233], v[2:5], v[226:229], v[230:233]
	v_max_i32_e32 v250, 0, v242
	v_fmac_f32_e32 v30, v250, v23
	v_max_i32_e32 v225, 0, v243
	v_fmac_f32_e32 v31, v225, v23
	v_mfma_f32_16x16x32_bf16 v[234:237], v[10:13], v[226:229], v[234:237]
	v_max_i32_e32 v250, 0, v244
	v_fmac_f32_e32 v28, v250, v23
	v_max_i32_e32 v225, 0, v245
	v_fmac_f32_e32 v29, v225, v23
	s_waitcnt lgkmcnt(4)
	v_mfma_f32_16x16x32_bf16 v[238:241], v[6:9], v[178:181], 0
	ds_read_b128 v[216:219], v173 offset:12288
	ds_read_b128 v[226:229], v173 offset:13312
	v_max_i32_e32 v250, 0, v230
	v_fmac_f32_e32 v34, v250, v24
	v_max_i32_e32 v225, 0, v231
	v_fmac_f32_e32 v35, v225, v24
	v_mfma_f32_16x16x32_bf16 v[242:245], v[14:17], v[178:181], 0
	v_max_i32_e32 v250, 0, v232
	v_fmac_f32_e32 v32, v250, v24
	v_max_i32_e32 v225, 0, v233
	v_fmac_f32_e32 v33, v225, v24
	v_mfma_f32_16x16x32_bf16 v[238:241], v[2:5], v[182:185], v[238:241]
	v_max_i32_e32 v250, 0, v234
	v_fmac_f32_e32 v30, v250, v24
	v_max_i32_e32 v225, 0, v235
	v_fmac_f32_e32 v31, v225, v24
	v_mfma_f32_16x16x32_bf16 v[242:245], v[10:13], v[182:185], v[242:245]
	v_max_i32_e32 v250, 0, v236
	v_fmac_f32_e32 v28, v250, v24
	v_max_i32_e32 v225, 0, v237
	v_fmac_f32_e32 v29, v225, v24
	s_waitcnt lgkmcnt(4)
	v_mfma_f32_16x16x32_bf16 v[230:233], v[6:9], v[200:203], 0
	ds_read_b128 v[178:181], v173 offset:14336
	ds_read_b128 v[182:185], v173 offset:15360
	v_max_i32_e32 v250, 0, v238
	v_fmac_f32_e32 v34, v250, v25
	v_max_i32_e32 v225, 0, v239
	v_fmac_f32_e32 v35, v225, v25
	v_mfma_f32_16x16x32_bf16 v[234:237], v[14:17], v[200:203], 0
	v_max_i32_e32 v250, 0, v240
	v_fmac_f32_e32 v32, v250, v25
	v_max_i32_e32 v225, 0, v241
	v_fmac_f32_e32 v33, v225, v25
	v_mfma_f32_16x16x32_bf16 v[230:233], v[2:5], v[204:207], v[230:233]
	v_max_i32_e32 v250, 0, v242
	v_fmac_f32_e32 v30, v250, v25
	v_max_i32_e32 v225, 0, v243
	v_fmac_f32_e32 v31, v225, v25
	v_mfma_f32_16x16x32_bf16 v[234:237], v[10:13], v[204:207], v[234:237]
	v_max_i32_e32 v250, 0, v244
	v_fmac_f32_e32 v28, v250, v25
	v_max_i32_e32 v225, 0, v245
	v_fmac_f32_e32 v29, v225, v25
	s_waitcnt lgkmcnt(4)
	v_mfma_f32_16x16x32_bf16 v[238:241], v[6:9], v[208:211], 0
	v_max_i32_e32 v250, 0, v230
	v_fmac_f32_e32 v34, v250, v18
	v_max_i32_e32 v225, 0, v231
	v_fmac_f32_e32 v35, v225, v18
	v_mfma_f32_16x16x32_bf16 v[242:245], v[14:17], v[208:211], 0
	v_max_i32_e32 v250, 0, v232
	v_fmac_f32_e32 v32, v250, v18
	v_max_i32_e32 v225, 0, v233
	v_fmac_f32_e32 v33, v225, v18
	v_mfma_f32_16x16x32_bf16 v[238:241], v[2:5], v[212:215], v[238:241]
	v_max_i32_e32 v250, 0, v234
	v_fmac_f32_e32 v30, v250, v18
	v_max_i32_e32 v225, 0, v235
	v_fmac_f32_e32 v31, v225, v18
	v_mfma_f32_16x16x32_bf16 v[242:245], v[10:13], v[212:215], v[242:245]
	v_max_i32_e32 v250, 0, v236
	v_fmac_f32_e32 v28, v250, v18
	v_max_i32_e32 v225, 0, v237
	v_fmac_f32_e32 v29, v225, v18
	s_waitcnt lgkmcnt(2)
	v_mfma_f32_16x16x32_bf16 v[230:233], v[6:9], v[216:219], 0
	v_max_i32_e32 v250, 0, v238
	v_fmac_f32_e32 v34, v250, v19
	v_max_i32_e32 v225, 0, v239
	v_fmac_f32_e32 v35, v225, v19
	v_mfma_f32_16x16x32_bf16 v[234:237], v[14:17], v[216:219], 0
	v_max_i32_e32 v250, 0, v240
	v_fmac_f32_e32 v32, v250, v19
	v_max_i32_e32 v225, 0, v241
	v_fmac_f32_e32 v33, v225, v19
	v_mfma_f32_16x16x32_bf16 v[230:233], v[2:5], v[226:229], v[230:233]
	v_max_i32_e32 v250, 0, v242
	v_fmac_f32_e32 v30, v250, v19
	v_max_i32_e32 v225, 0, v243
	v_fmac_f32_e32 v31, v225, v19
	v_mfma_f32_16x16x32_bf16 v[234:237], v[10:13], v[226:229], v[234:237]
	v_max_i32_e32 v250, 0, v244
	v_fmac_f32_e32 v28, v250, v19
	v_max_i32_e32 v225, 0, v245
	v_fmac_f32_e32 v29, v225, v19
	s_waitcnt lgkmcnt(0)
	v_mfma_f32_16x16x32_bf16 v[238:241], v[6:9], v[178:181], 0
	ds_read_b128 v[200:203], v173
	ds_read_b128 v[204:207], v173 offset:1024
	ds_read_b128 v[208:211], v173 offset:2048
	ds_read_b128 v[212:215], v173 offset:3072
	ds_read_b128 v[216:219], v173 offset:4096
	ds_read_b128 v[226:229], v173 offset:5120
	v_max_i32_e32 v250, 0, v230
	v_fmac_f32_e32 v34, v250, v20
	v_max_i32_e32 v225, 0, v231
	v_fmac_f32_e32 v35, v225, v20
	v_mfma_f32_16x16x32_bf16 v[242:245], v[14:17], v[178:181], 0
	v_max_i32_e32 v250, 0, v232
	v_fmac_f32_e32 v32, v250, v20
	v_max_i32_e32 v225, 0, v233
	v_fmac_f32_e32 v33, v225, v20
	v_mfma_f32_16x16x32_bf16 v[238:241], v[2:5], v[182:185], v[238:241]
	v_max_i32_e32 v250, 0, v234
	v_fmac_f32_e32 v30, v250, v20
	v_max_i32_e32 v225, 0, v235
	v_fmac_f32_e32 v31, v225, v20
	v_mfma_f32_16x16x32_bf16 v[242:245], v[10:13], v[182:185], v[242:245]
	v_max_i32_e32 v250, 0, v236
	v_fmac_f32_e32 v28, v250, v20
	v_max_i32_e32 v225, 0, v237
	v_fmac_f32_e32 v29, v225, v20
	v_max_i32_e32 v250, 0, v238
	v_fmac_f32_e32 v34, v250, v21
	v_max_i32_e32 v225, 0, v239
	v_fmac_f32_e32 v35, v225, v21
	v_max_i32_e32 v250, 0, v240
	v_fmac_f32_e32 v32, v250, v21
	v_max_i32_e32 v225, 0, v241
	v_fmac_f32_e32 v33, v225, v21
	v_max_i32_e32 v250, 0, v242
	v_fmac_f32_e32 v30, v250, v21
	v_max_i32_e32 v225, 0, v243
	v_fmac_f32_e32 v31, v225, v21
	v_max_i32_e32 v250, 0, v244
	v_fmac_f32_e32 v28, v250, v21
	v_max_i32_e32 v225, 0, v245
	v_fmac_f32_e32 v29, v225, v21
	v_lshl_add_u64 v[2:3], v[26:27], 0, s[8:9]
	s_lshl_b32 s8, s11, 4
	s_ashr_i32 s9, s8, 31
	s_lshl_b64 s[8:9], s[8:9], 7
	v_lshl_add_u64 v[10:11], v[26:27], 0, s[8:9]
	global_load_dwordx4 v[6:9], v[2:3], off
	s_nop 0
	global_load_dwordx4 v[2:5], v[2:3], off offset:64
	s_nop 0
	global_load_dwordx4 v[14:17], v[10:11], off
	s_nop 0
	global_load_dwordx4 v[10:13], v[10:11], off offset:64
	s_cmp_eq_u32 s10, s12
	v_ashrrev_i32_e32 v178, 31, v34
	s_cbranch_scc1 .LBB0_1317
	v_bitop3_b32 v18, v178, v34, s76 bitop3:0x36
	v_add_u32_e32 v19, v246, v18
	v_lshrrev_b32_e32 v20, 21, v19
	v_lshrrev_b32_e32 v19, 3, v20
	v_bitop3_b32 v19, v19, v20, 28 bitop3:0x6c
	v_lshl_add_u32 v19, v19, 2, v40
	ds_add_u32 v19, v186
	v_ashrrev_i32_e32 v19, 31, v35
	v_bitop3_b32 v19, v19, v35, s76 bitop3:0x36
	v_add_u32_e32 v20, v246, v19
	v_lshrrev_b32_e32 v21, 21, v20
	v_lshrrev_b32_e32 v20, 3, v21
	v_bitop3_b32 v20, v20, v21, 28 bitop3:0x6c
	v_lshl_add_u32 v20, v20, 2, v40
	ds_add_u32 v20, v186
	v_ashrrev_i32_e32 v20, 31, v32
	v_bitop3_b32 v20, v20, v32, s76 bitop3:0x36
	v_add_u32_e32 v21, v246, v20
	v_lshrrev_b32_e32 v22, 21, v21
	v_lshrrev_b32_e32 v21, 3, v22
	v_bitop3_b32 v21, v21, v22, 28 bitop3:0x6c
	v_lshl_add_u32 v21, v21, 2, v40
	ds_add_u32 v21, v186
	v_ashrrev_i32_e32 v21, 31, v33
	v_bitop3_b32 v23, v21, v33, s76 bitop3:0x36
	v_add_u32_e32 v21, v246, v23
	v_lshrrev_b32_e32 v22, 21, v21
	v_lshrrev_b32_e32 v21, 3, v22
	v_bitop3_b32 v21, v21, v22, 28 bitop3:0x6c
	v_lshl_add_u32 v21, v21, 2, v40
	ds_add_u32 v21, v186
	s_mov_b64 s[10:11], 0
	v_mov_b32_e32 v25, 0
	v_mov_b32_e32 v24, 0
	v_mov_b32_e32 v22, 0
	v_mov_b32_e32 v21, 0
	s_mov_b64 s[8:9], 0
	s_mov_b64 vcc, vcc
	s_cbranch_vccz .LBB0_1299
	v_ashrrev_i32_e32 v21, 31, v30
	v_bitop3_b32 v21, v21, v30, s76 bitop3:0x36
	v_add_u32_e32 v22, v246, v21
	v_lshrrev_b32_e32 v24, 21, v22
	v_lshrrev_b32_e32 v22, 3, v24
	v_bitop3_b32 v22, v22, v24, 28 bitop3:0x6c
	v_lshl_add_u32 v22, v22, 2, v40
	ds_add_u32 v22, v186
	v_ashrrev_i32_e32 v22, 31, v31
	v_bitop3_b32 v22, v22, v31, s76 bitop3:0x36
	v_add_u32_e32 v24, v246, v22
	v_lshrrev_b32_e32 v25, 21, v24
	v_lshrrev_b32_e32 v24, 3, v25
	v_bitop3_b32 v24, v24, v25, 28 bitop3:0x6c
	v_lshl_add_u32 v24, v24, 2, v40
	ds_add_u32 v24, v186
	v_ashrrev_i32_e32 v24, 31, v28
	v_bitop3_b32 v24, v24, v28, s76 bitop3:0x36
	v_add_u32_e32 v25, v246, v24
	v_lshrrev_b32_e32 v177, 21, v25
	v_lshrrev_b32_e32 v25, 3, v177
	v_bitop3_b32 v25, v25, v177, 28 bitop3:0x6c
	v_lshl_add_u32 v25, v25, 2, v40
	ds_add_u32 v25, v186
	v_ashrrev_i32_e32 v25, 31, v29
	v_bitop3_b32 v177, v25, v29, s76 bitop3:0x36
	s_mov_b64 s[8:9], -1
	v_mov_b32_e32 v25, v177
